# quad seams: L1 invalidate issued at arrival (before the poll)
# baseline (speedup 1.0000x reference)
; __device__ __forceinline__ unsigned xb_ld(unsigned* p)              { return __hip_atomic_load(p, __ATOMIC_RELAXED, __HIP_MEMORY_SCOPE_AGENT); }
; __device__ __forceinline__ unsigned xb_add(unsigned* p, unsigned v) { return __hip_atomic_fetch_add(p, v, __ATOMIC_RELAXED, __HIP_MEMORY_SCOPE_AGENT); }
; #define XB_SPIN(cond, bar) do { unsigned _sp = 0; while (cond) { __builtin_amdgcn_s_sleep(1); \
;     if ((++_sp & 255u) == 0u) { if (xb_ld(&(bar)[XB_TMO])) break; if (_sp > XB_SPIN_CAP) { atomicAdd(&(bar)[XB_TMO], 1u); break; } } } } while (0)
; __device__ __forceinline__ void xcd_barrier(const XcdBarrier& b) {
;     asm volatile("s_waitcnt vmcnt(0)" ::: "memory");
;     __syncthreads();
;     if (threadIdx.x == 0) {
;         unsigned* bar = b.bar;
;         __builtin_amdgcn_s_waitcnt(0);
;         unsigned nloc = b.st[0], nx = b.st[1];
;         if (nloc == 0u) { xcd_barrier_complete(bar, b.x, b.gsize, nloc, nx); b.st[0] = nloc; b.st[1] = nx; }
;         const unsigned old = xb_add(&bar[XB_XSUB(b.x)], 1u);
;         const unsigned gen = old / nloc;
;         if (old + 1u == (gen + 1u) * nloc) {
;             __builtin_amdgcn_fence(__ATOMIC_RELEASE, "agent");
;             asm volatile("s_waitcnt vmcnt(0)" ::: "memory");
;             const unsigned og = xb_add(&bar[XB_TOP], 1u);
;             const unsigned tg = og / nx;
;             if (og + 1u == (tg + 1u) * nx) xb_add(&bar[XB_TOPGEN], 1u);
;             else XB_SPIN(xb_ld(&bar[XB_TOPGEN]) == tg, bar);
;             __builtin_amdgcn_fence(__ATOMIC_ACQUIRE, "agent");
;             xb_add(&bar[XB_XGEN(b.x)], 1u);
;             asm volatile("s_waitcnt vmcnt(0)" ::: "memory");
;         } else {
;             XB_SPIN(xb_ld(&bar[XB_XGEN(b.x)]) == gen, bar);
;             __builtin_amdgcn_fence(__ATOMIC_ACQUIRE, "agent");
;             asm volatile("s_waitcnt vmcnt(0)" ::: "memory");
;         }
;     }
;     __syncthreads();
; }
.LBB0_457:
	s_waitcnt vmcnt(0)
	s_barrier
	s_and_saveexec_b64 s[0:1], s[90:91]
	s_xor_b64 s[0:1], exec, s[0:1]
	s_cbranch_execz .LBB0_510
	s_cmp_lg_u32 s100, 0
	s_cbranch_scc1 .Lq4_slow
	v_readlane_b32 s4, v250, 14
	v_readlane_b32 s5, v250, 15
	s_and_b32 s6, s101, 7
	s_lshl_b32 s6, s6, 3
	s_bfe_u32 s7, s101, 0x30003
	s_or_b32 s6, s6, s7
	s_lshl_b32 s6, s6, 7
	s_add_i32 s6, s6, 0x19000
	v_mov_b32_e32 v1, s6
	v_mov_b32_e32 v2, 1
	s_mov_b32 s7, 0
	s_nop 4
	global_atomic_add v1, v2, s[4:5]
	buffer_inv sc1

; __device__ __forceinline__ unsigned xb_ld(unsigned* p)              { return __hip_atomic_load(p, __ATOMIC_RELAXED, __HIP_MEMORY_SCOPE_AGENT); }
; #define XB_SPIN(cond, bar) do { unsigned _sp = 0; while (cond) { __builtin_amdgcn_s_sleep(1); \
;     if ((++_sp & 255u) == 0u) { if (xb_ld(&(bar)[XB_TMO])) break; if (_sp > XB_SPIN_CAP) { atomicAdd(&(bar)[XB_TMO], 1u); break; } } } } while (0)
; __device__ __forceinline__ void xcd_barrier(const XcdBarrier& b) {
;     ...
;             XB_SPIN(xb_ld(&bar[XB_XGEN(b.x)]) == gen, bar);
;             __builtin_amdgcn_fence(__ATOMIC_ACQUIRE, "agent");
;             asm volatile("s_waitcnt vmcnt(0)" ::: "memory");
.Lq4_ok:
	s_branch .LBB0_510

; __device__ __forceinline__ unsigned xb_ld(unsigned* p)              { return __hip_atomic_load(p, __ATOMIC_RELAXED, __HIP_MEMORY_SCOPE_AGENT); }
; __device__ __forceinline__ unsigned xb_add(unsigned* p, unsigned v) { return __hip_atomic_fetch_add(p, v, __ATOMIC_RELAXED, __HIP_MEMORY_SCOPE_AGENT); }
; #define XB_SPIN(cond, bar) do { unsigned _sp = 0; while (cond) { __builtin_amdgcn_s_sleep(1); \
;     if ((++_sp & 255u) == 0u) { if (xb_ld(&(bar)[XB_TMO])) break; if (_sp > XB_SPIN_CAP) { atomicAdd(&(bar)[XB_TMO], 1u); break; } } } } while (0)
; __device__ __forceinline__ void xcd_barrier(const XcdBarrier& b) {
;     asm volatile("s_waitcnt vmcnt(0)" ::: "memory");
;     __syncthreads();
;     if (threadIdx.x == 0) {
;         unsigned* bar = b.bar;
;         __builtin_amdgcn_s_waitcnt(0);
;         unsigned nloc = b.st[0], nx = b.st[1];
;         if (nloc == 0u) { xcd_barrier_complete(bar, b.x, b.gsize, nloc, nx); b.st[0] = nloc; b.st[1] = nx; }
;         const unsigned old = xb_add(&bar[XB_XSUB(b.x)], 1u);
;         const unsigned gen = old / nloc;
;         if (old + 1u == (gen + 1u) * nloc) {
;             __builtin_amdgcn_fence(__ATOMIC_RELEASE, "agent");
;             asm volatile("s_waitcnt vmcnt(0)" ::: "memory");
;             const unsigned og = xb_add(&bar[XB_TOP], 1u);
;             const unsigned tg = og / nx;
;             if (og + 1u == (tg + 1u) * nx) xb_add(&bar[XB_TOPGEN], 1u);
;             else XB_SPIN(xb_ld(&bar[XB_TOPGEN]) == tg, bar);
;             __builtin_amdgcn_fence(__ATOMIC_ACQUIRE, "agent");
;             xb_add(&bar[XB_XGEN(b.x)], 1u);
;             asm volatile("s_waitcnt vmcnt(0)" ::: "memory");
;         } else {
;             XB_SPIN(xb_ld(&bar[XB_XGEN(b.x)]) == gen, bar);
;             __builtin_amdgcn_fence(__ATOMIC_ACQUIRE, "agent");
;             asm volatile("s_waitcnt vmcnt(0)" ::: "memory");
;         }
;     }
;     __syncthreads();
; }
.LBB0_638:
	s_or_b64 exec, exec, s[4:5]
	s_waitcnt vmcnt(0)
	s_barrier
	s_and_saveexec_b64 s[0:1], s[90:91]
	v_readlane_b32 s62, v250, 42
	v_readlane_b32 s64, v250, 40
	v_readlane_b32 s63, v250, 43
	v_readlane_b32 s65, v250, 41
	s_cbranch_execz .LBB0_690
	s_cmp_lg_u32 s100, 0
	s_cbranch_scc1 .Lq6_slow
	v_readlane_b32 s4, v250, 14
	v_readlane_b32 s5, v250, 15
	s_and_b32 s6, s101, 7
	s_lshl_b32 s6, s6, 3
	s_bfe_u32 s7, s101, 0x30003
	s_or_b32 s6, s6, s7
	s_lshl_b32 s6, s6, 7
	s_add_i32 s6, s6, 0x1b000
	v_mov_b32_e32 v1, s6
	v_mov_b32_e32 v2, 1
	s_mov_b32 s7, 0
	s_nop 4
	global_atomic_add v1, v2, s[4:5]
	buffer_inv sc1
